# speedup vs baseline: 1.0745x; 1.0070x over previous
; __device__ __forceinline__ int v_st(int k, int c) { const int kk = (k & ~0xC) | ((k & 4) << 1) | ((k & 8) >> 1); return ((kk >> 3) * 4 + (c >> 5)) * 512 + ((kk & 7) * 32 + (c & 31)) * 2; }
; __device__ __forceinline__ int v_rd_base(int lane) { return ((lane & 3) << 3) | (((lane >> 2) & 3) << 6) | (((lane >> 4) & 1) << 5) | (((lane >> 5) & 1) << 8); }
; #define SLOAD(i, key0) do { sr_[i].v = *reinterpret_cast<const bf16x8*>(&Vh[(long)((key0) + vr) * ldv + vc]); \
;     sr_[i].k0 = *reinterpret_cast<const bf16x8*>(&Kh[(long)((key0) + kr0) * ldk + kc0]); \
;     if (k2) sr_[i].k1 = *reinterpret_cast<const bf16x8*>(&Kh[(long)((key0) + kr1) * ldk + kc1]); } while (0)
; #define SWRITE(b, i) do { *(bf16x8*)((char*)V_lds + (b) * SHM_V + vst) = sr_[i].v; \
;     *(bf16x8*)((char*)K_lds + (b) * SHM_K + ksw0) = sr_[i].k0; \
;     if (k2) *(bf16x8*)((char*)K_lds + (b) * SHM_K + ksw1) = sr_[i].k1; } while (0)
; template <int DQK, bool FIX>
; __device__ __forceinline__ void attn_item(const bf16* Qb, const bf16* __restrict__ Kh, const bf16* __restrict__ Vh,
;                                           u16* Ob, int q0, int L, int NT, char* lds, float mC) {
;     ...
;   float m_reg = -1e30f, l_reg = 0; f32x16 o[2] = {}; bf16x8 qr[ND];
;   __syncthreads();
;   { int qrow = q0 + wid * 32 + r32; if (qrow > L - 1) qrow = L - 1;
;     const bf16* Qw = Qb + (long)qrow * ldq + hi * 8;
; #pragma unroll
;     for (int d0 = 0; d0 < ND; ++d0) qr[d0] = *reinterpret_cast<const bf16x8*>(Qw + d0 * 16); }
;   const int vr = tid >> 3, vc = (tid & 7) * 8, vst = v_st(vr, vc);
;   const int kr0 = tid / KCH, kc0 = (tid % KCH) * 8, kr1 = (tid + 512) / KCH, kc1 = ((tid + 512) % KCH) * 8;
;   const bool k2 = (DQK == 96) && (tid < 256);
;   const int ksw0 = KSWZ(kr0, kc0 * 2), ksw1 = KSWZ(kr1, kc1 * 2);
;   const int vb0 = (int)(uintptr_t)V_lds + v_rd_base(lane);
;   struct { bf16x8 v, k0, k1; } sr_[2];
;     ...
;   f32x16 pA0, pA1, pB0, pB1; float mnA = 0.f, mnB = 0.f, alA = 1.f, alB = 1.f; bf16x8 pa0, pa1, pa2, pa3;
;   constexpr int SE = 0, SO = 1;
;   const bool act = (q0 + wid * 32) < L;
;   SLOAD(SE, 0); asm volatile("s_waitcnt vmcnt(0)" ::: "memory"); SWRITE(0, SE); __syncthreads();
;   if (act) { qkt<DQK>(pA0, pA1, K_lds, qr, r32, hi, 0, L); partialSM<DQK, FIX>(pA0, pA1, m_reg, mnA, alA, mC); }
;   SLOAD(SO, KVBLK); if (2 < NT) SLOAD(SE, 2 * KVBLK);
;   SWAIT(); SWRITE(1, SO); __syncthreads();
.LBB0_829:
	v_writelane_b32 v254, s18, 59
	v_writelane_b32 v255, s16, 0
	v_writelane_b32 v255, s19, 1
	s_or_b64 exec, exec, s[2:3]
	v_lshlrev_b64 v[2:3], 8, v[18:19]
	v_mov_b32_e32 v29, v1
	v_lshl_add_u64 v[2:3], s[14:15], 0, v[2:3]
	v_lshl_add_u64 v[2:3], v[2:3], 0, v[28:29]
	s_movk_i32 s2, 0x4000
	v_add_co_u32_e32 v4, vcc, s2, v2
	v_lshlrev_b64 v[18:19], 1, v[26:27]
	s_nop 0
	v_addc_co_u32_e32 v5, vcc, 0, v3, vcc
	global_load_dwordx4 v[68:71], v[4:5], off
	v_lshlrev_b64 v[4:5], 8, v[22:23]
	v_lshl_add_u64 v[4:5], s[12:13], 0, v[4:5]
	v_lshl_add_u64 v[4:5], v[4:5], 0, v[18:19]
	v_add_co_u32_e32 v6, vcc, s2, v4
	s_mov_b32 s2, 0x8000
	s_nop 0
	v_addc_co_u32_e32 v7, vcc, 0, v5, vcc
	v_add_co_u32_e32 v4, vcc, s2, v4
	global_load_dwordx4 v[26:29], v[6:7], off
	s_nop 0
	v_addc_co_u32_e32 v5, vcc, 0, v5, vcc
	v_add_co_u32_e32 v2, vcc, s2, v2
	global_load_dwordx4 v[204:207], v[4:5], off
	s_nop 0
	v_addc_co_u32_e32 v3, vcc, 0, v3, vcc
	global_load_dwordx4 v[114:117], v[2:3], off
	v_add_co_u32_e32 v6, vcc, 0x4000, v4
	s_nop 1
	v_addc_co_u32_e32 v7, vcc, 0, v5, vcc
	global_load_dwordx4 v[118:121], v[6:7], off
	v_and_b32_e32 v159, 63, v158
	v_lshlrev_b32_e32 v72, 4, v159
	v_lshlrev_b32_e32 v67, 3, v159
	v_lshlrev_b32_e32 v73, 1, v159
	s_cmp_lg_u32 0, -1
	v_lshl_add_u64 v[22:23], v[24:25], 0, s[6:7]
	v_and_b32_e32 v24, 7, v158
	v_and_b32_e32 v72, 0xc0, v72
	v_readlane_b32 s12, v254, 35
	v_lshl_add_u64 v[20:21], v[20:21], 0, s[6:7]
	v_mov_b32_e32 v25, v1
	v_and_b32_e32 v73, 32, v73
	v_and_b32_e32 v74, 0x100, v67
	s_cselect_b32 s2, 0, 0
	v_lshl_add_u64 v[18:19], v[22:23], 0, v[18:19]
	v_lshlrev_b32_e32 v24, 4, v24
	v_and_or_b32 v22, v67, 24, v72
	v_readlane_b32 s13, v254, 36
	v_add_u32_e32 v66, 0, v66
	v_add_u32_e32 v31, 0, v31
	v_add_u32_e32 v32, 0, v32
	v_add_u32_e32 v33, 0, v33
	v_mov_b32_e32 v16, v1
	v_mov_b32_e32 v17, v1
	s_add_i32 s3, s2, 0x4000
	v_readlane_b32 s14, v254, 37
	v_readlane_b32 s15, v254, 38
	v_lshl_add_u64 v[146:147], s[12:13], 0, v[18:19]
	v_lshl_add_u64 v[18:19], v[20:21], 0, v[24:25]
	v_or3_b32 v20, v22, v73, v74
	s_waitcnt vmcnt(2)
	v_mov_b32_e32 v2, v1
	v_mov_b32_e32 v3, v1
	v_mov_b32_e32 v4, v1
	v_mov_b32_e32 v5, v1
	v_mov_b32_e32 v6, v1
	v_mov_b32_e32 v7, v1
	v_mov_b32_e32 v8, v1
	v_mov_b32_e32 v9, v1
	v_mov_b32_e32 v10, v1
	v_mov_b32_e32 v11, v1
	v_mov_b32_e32 v12, v1
	v_mov_b32_e32 v13, v1
	v_mov_b32_e32 v14, v1
	v_mov_b32_e32 v15, v1
	v_add_u32_e32 v167, v66, v30
	v_add_u32_e32 v168, v31, v30
	v_add_u32_e32 v169, v32, v30
	v_lshl_add_u64 v[148:149], s[14:15], 0, v[18:19]
	v_add_u32_e32 v166, s2, v20
	v_add_u32_e32 v170, s3, v20
	v_add_u32_e32 v171, v33, v30
	v_mov_b64_e32 v[96:97], v[16:17]
	s_mov_b32 s73, 4
	s_mov_b32 s78, 0
	v_lshlrev_b32_e32 v162, 2, v155
	v_mov_b32_e32 v163, 0
	s_sub_i32 s79, s96, 64
	s_sub_i32 s72, s96, 32
	s_waitcnt vmcnt(3)
	ds_write_b128 v160, v[68:71] offset:16384
	s_waitcnt vmcnt(2)
	ds_write_b128 v161, v[26:29] offset:49152
	v_mov_b64_e32 v[32:33], v[16:17]
	v_mov_b64_e32 v[80:81], v[16:17]
	v_mov_b64_e32 v[30:31], v[14:15]
	v_mov_b64_e32 v[28:29], v[12:13]
	v_mov_b64_e32 v[26:27], v[10:11]
	v_mov_b64_e32 v[24:25], v[8:9]
	v_mov_b64_e32 v[22:23], v[6:7]
	v_mov_b64_e32 v[20:21], v[4:5]
	v_mov_b64_e32 v[18:19], v[2:3]
	v_mov_b64_e32 v[78:79], v[14:15]
	v_mov_b64_e32 v[76:77], v[12:13]
	v_mov_b64_e32 v[74:75], v[10:11]
	v_mov_b64_e32 v[72:73], v[8:9]
	v_mov_b64_e32 v[70:71], v[6:7]
	v_mov_b64_e32 v[68:69], v[4:5]
	v_mov_b64_e32 v[66:67], v[2:3]
	v_mov_b64_e32 v[94:95], v[14:15]
	v_mov_b64_e32 v[92:93], v[12:13]
	v_mov_b64_e32 v[90:91], v[10:11]
	v_mov_b64_e32 v[88:89], v[8:9]
	v_mov_b64_e32 v[86:87], v[6:7]
	v_mov_b64_e32 v[84:85], v[4:5]
	v_mov_b64_e32 v[82:83], v[2:3]
	s_waitcnt lgkmcnt(0)
	s_barrier
	s_waitcnt vmcnt(2)
	ds_write_b128 v161, v[204:207] offset:32768
	v_mov_b32_e32 v202, 0
	v_readfirstlane_b32 s74, v146
	v_readfirstlane_b32 s75, v147
	v_readfirstlane_b32 s80, v148
	v_readfirstlane_b32 s81, v149
	s_nop 3
	v_subrev_u32_e32 v210, s74, v146
	v_subrev_u32_e32 v211, s80, v148
	s_add_u32 s74, s74, s4
	s_addc_u32 s75, s75, s5
	s_add_u32 s74, s74, 0x119d0000
	s_addc_u32 s75, s75, 0
	s_add_u32 s76, s74, 0x4000
	s_addc_u32 s77, s75, 0
	s_add_u32 s80, s80, s4
	s_addc_u32 s81, s81, s5
	s_add_u32 s80, s80, 0x2ced0000
	s_addc_u32 s81, s81, 0
	s_add_u32 s84, s80, 0x4000
	s_addc_u32 s85, s81, 0
	s_branch .LBB0_832

; #define SBAR() __builtin_amdgcn_sched_barrier(0)
; #define SLOAD(i, key0) do { sr_[i].v = *reinterpret_cast<const bf16x8*>(&Vh[(long)((key0) + vr) * ldv + vc]); \
;     sr_[i].k0 = *reinterpret_cast<const bf16x8*>(&Kh[(long)((key0) + kr0) * ldk + kc0]); \
;     if (k2) sr_[i].k1 = *reinterpret_cast<const bf16x8*>(&Kh[(long)((key0) + kr1) * ldk + kc1]); } while (0)
; #define SWRITE(b, i) do { *(bf16x8*)((char*)V_lds + (b) * SHM_V + vst) = sr_[i].v; \
;     *(bf16x8*)((char*)K_lds + (b) * SHM_K + ksw0) = sr_[i].k0; \
;     if (k2) *(bf16x8*)((char*)K_lds + (b) * SHM_K + ksw1) = sr_[i].k1; } while (0)
; #define SWAIT() asm volatile("s_waitcnt vmcnt(2)" ::: "memory")
; #define RESC(a) do { if (__any((a) < 1.f)) { if (hi == 0) al_l[r32] = (a); asm volatile("s_waitcnt lgkmcnt(0)" ::: "memory"); \
;     _Pragma("unroll") for (int d = 0; d < 2; ++d) _Pragma("unroll") for (int r = 0; r < 16; ++r) o[d][r] *= al_l[crow(r, hi)]; } } while (0)
; template <int DQK, bool FIX>
; __device__ __forceinline__ void attn_item(const bf16* Qb, const bf16* __restrict__ Kh, const bf16* __restrict__ Vh,
;                                           u16* Ob, int q0, int L, int NT, char* lds, float mC) {
;     ...
;   for (int j = 1; j + 1 < NT; j += 2) {
;     if (act) { SBAR(); qkt<DQK>(pB0, pB1, (bf16*)((char*)K_lds + SHM_K), qr, r32, hi, j * KVBLK, L);
;       finishSM(pA0, pA1, alA, l_reg, pa0, pa1, pa2, pa3); SBAR(); }
;     SLOAD(SO, (j + 2) * KVBLK); SBAR();
;     ...
;     __syncthreads(); SWAIT(); SWRITE(1, SO);
;     if (act) { RESC(alA); } __syncthreads();
;   }
.LBB0_831:
	s_or_b64 exec, exec, s[6:7]
	s_waitcnt lgkmcnt(0)
	s_barrier
	s_waitcnt vmcnt(2)
	s_mov_b64 s[6:7], 0x8000
	s_addk_i32 s78, 0x80
	v_lshl_add_u64 v[146:147], v[146:147], 0, s[6:7]
	v_lshl_add_u64 v[148:149], v[148:149], 0, s[6:7]
	s_add_i32 s73, s73, 2
	s_add_u32 s74, s74, 0x8000
	s_addc_u32 s75, s75, 0
	s_add_u32 s76, s76, 0x8000
	s_addc_u32 s77, s77, 0
	s_add_u32 s80, s80, 0x8000
	s_addc_u32 s81, s81, 0
	s_add_u32 s84, s84, 0x8000
	s_addc_u32 s85, s85, 0
	s_and_b64 vcc, exec, s[2:3]
	s_cbranch_vccz .Lt64b_w
	s_waitcnt vmcnt(0)

; #define SBAR() __builtin_amdgcn_sched_barrier(0)
; #define SLOAD(i, key0) do { sr_[i].v = *reinterpret_cast<const bf16x8*>(&Vh[(long)((key0) + vr) * ldv + vc]); \
;     sr_[i].k0 = *reinterpret_cast<const bf16x8*>(&Kh[(long)((key0) + kr0) * ldk + kc0]); \
;     if (k2) sr_[i].k1 = *reinterpret_cast<const bf16x8*>(&Kh[(long)((key0) + kr1) * ldk + kc1]); } while (0)
; __device__ __forceinline__ void finishSM(f32x16& p0, f32x16& p1, float alpha, float& l_reg, bf16x8& pa0, bf16x8& pa1, bf16x8& pa2, bf16x8& pa3) {
; #pragma unroll
;   for (int r = 0; r < 16; ++r) p1[r] = __builtin_amdgcn_exp2f(p1[r]);
;   float ps = 0;
; #pragma unroll
;   for (int r = 0; r < 16; ++r) ps += p0[r];
; #pragma unroll
;   for (int r = 0; r < 16; ++r) ps += p1[r];
;   { auto rr = __builtin_amdgcn_permlane32_swap(__float_as_uint(ps), __float_as_uint(ps), false, false);
;     ps = __uint_as_float(rr[0]) + __uint_as_float(rr[1]); }
;   l_reg = l_reg * alpha + ps;
;     ...
;   PK4(p0, 0, pa0); PK4(p0, 8, pa1); PK4(p1, 0, pa2); PK4(p1, 8, pa3);
; template <int DQK, bool FIX>
; __device__ __forceinline__ void attn_item(const bf16* Qb, const bf16* __restrict__ Kh, const bf16* __restrict__ Vh,
;                                           u16* Ob, int q0, int L, int NT, char* lds, float mC) {
;     ...
;     if (act) { SBAR(); qkt<DQK>(pB0, pB1, (bf16*)((char*)K_lds + SHM_K), qr, r32, hi, j * KVBLK, L);
;       finishSM(pA0, pA1, alA, l_reg, pa0, pa1, pa2, pa3); SBAR(); }
;     SLOAD(SO, (j + 2) * KVBLK); SBAR();
;     if (act) { pv_d0(o, vb0, pa0, pa1, pa2, pa3); partialSM<DQK, FIX>(pB0, pB1, m_reg, mnB, alB, mC); }
.LBB0_832:
	s_and_saveexec_b64 s[2:3], s[8:9]
	s_cbranch_execz .LBB0_838
	s_add_i32 s6, s78, 64
	s_cmp_le_u32 s6, s79
	s_cbranch_scc0 .Lslow64a
	s_and_b64 vcc, exec, s[10:11]
	s_cbranch_vccz .Lslow64a
	ds_read_b128 v[222:225], v167 offset:49152
	ds_read_b128 v[226:229], v168 offset:49152
	ds_read_b128 v[230:233], v167 offset:57344
	ds_read_b128 v[234:237], v168 offset:57344
	ds_read_b128 v[238:241], v169 offset:49152
	ds_read_b128 v[242:245], v169 offset:57344
	ds_read_b128 v[246:249], v171 offset:49152
	ds_read_b128 v[250:253], v171 offset:57344
	v_cvt_pk_bf16_f32 v130, v50, v51
	v_cvt_pk_bf16_f32 v131, v52, v53
	v_cvt_pk_bf16_f32 v132, v54, v55
	v_cvt_pk_bf16_f32 v133, v56, v57
	v_cvt_pk_bf16_f32 v134, v58, v59
	v_cvt_pk_bf16_f32 v135, v60, v61
	v_cvt_pk_bf16_f32 v136, v62, v63
	v_cvt_pk_bf16_f32 v137, v64, v65
	s_waitcnt lgkmcnt(7)
	v_mfma_f32_32x32x16_bf16 v[66:81], v[222:225], v[98:101], 0
	ds_read_b64_tr_b16 v[186:187], v166 offset:0
	ds_read_b64_tr_b16 v[188:189], v166 offset:2048
	ds_read_b64_tr_b16 v[190:191], v166 offset:4096
	ds_read_b64_tr_b16 v[192:193], v166 offset:6144
	v_exp_f32_e32 v34, v34
	v_exp_f32_e32 v35, v35
	v_add_f32_e32 v208, 0, v50
	v_add_f32_e32 v208, v51, v208
	s_waitcnt lgkmcnt(10)
	v_mfma_f32_32x32x16_bf16 v[66:81], v[226:229], v[102:105], v[66:81]
	ds_read_b64_tr_b16 v[194:195], v166 offset:8192
	ds_read_b64_tr_b16 v[196:197], v166 offset:10240
	ds_read_b64_tr_b16 v[198:199], v166 offset:12288
	ds_read_b64_tr_b16 v[200:201], v166 offset:14336
	v_exp_f32_e32 v36, v36
	v_exp_f32_e32 v37, v37
	v_exp_f32_e32 v38, v38
	v_add_f32_e32 v208, v52, v208
	s_waitcnt lgkmcnt(13)
	v_mfma_f32_32x32x16_bf16 v[82:97], v[230:233], v[98:101], 0
	v_exp_f32_e32 v39, v39
	v_exp_f32_e32 v40, v40
	v_add_f32_e32 v208, v53, v208
	v_add_f32_e32 v208, v54, v208
	s_waitcnt lgkmcnt(12)
	v_mfma_f32_32x32x16_bf16 v[82:97], v[234:237], v[102:105], v[82:97]
	v_exp_f32_e32 v41, v41
	v_exp_f32_e32 v42, v42
	v_exp_f32_e32 v43, v43
	v_add_f32_e32 v208, v55, v208
	s_waitcnt lgkmcnt(11)
	v_mfma_f32_32x32x16_bf16 v[66:81], v[238:241], v[106:109], v[66:81]
	v_exp_f32_e32 v44, v44
	v_exp_f32_e32 v45, v45
	v_add_f32_e32 v208, v56, v208
	v_add_f32_e32 v208, v57, v208
	s_waitcnt lgkmcnt(10)
	v_mfma_f32_32x32x16_bf16 v[82:97], v[242:245], v[106:109], v[82:97]
	ds_read_b64_tr_b16 v[222:223], v166 offset:512
	ds_read_b64_tr_b16 v[224:225], v166 offset:2560
	ds_read_b64_tr_b16 v[226:227], v166 offset:4608
	ds_read_b64_tr_b16 v[228:229], v166 offset:6656
	v_exp_f32_e32 v46, v46
	v_exp_f32_e32 v47, v47
	v_exp_f32_e32 v48, v48
	v_add_f32_e32 v208, v58, v208
	s_waitcnt lgkmcnt(13)
	v_mfma_f32_32x32x16_bf16 v[66:81], v[246:249], v[110:113], v[66:81]
	v_exp_f32_e32 v49, v49
	v_cvt_pk_bf16_f32 v138, v34, v35
	v_cvt_pk_bf16_f32 v139, v36, v37
	v_cvt_pk_bf16_f32 v140, v38, v39
	v_add_f32_e32 v208, v59, v208
	s_waitcnt lgkmcnt(12)
	v_mfma_f32_32x32x16_bf16 v[82:97], v[250:253], v[110:113], v[82:97]
	ds_read_b64_tr_b16 v[230:231], v166 offset:8704
	ds_read_b64_tr_b16 v[232:233], v166 offset:10752
	ds_read_b64_tr_b16 v[234:235], v166 offset:12800
	s_waitcnt lgkmcnt(14)
	ds_read_b64_tr_b16 v[236:237], v166 offset:14848
	v_cvt_pk_bf16_f32 v141, v40, v41
	v_cvt_pk_bf16_f32 v142, v42, v43
	v_cvt_pk_bf16_f32 v143, v44, v45
	v_cvt_pk_bf16_f32 v144, v46, v47
	v_cvt_pk_bf16_f32 v145, v48, v49
	v_add_f32_e32 v208, v60, v208
	v_add_f32_e32 v208, v61, v208
	s_or_b64 exec, exec, s[2:3]
	global_load_dwordx4 v[122:125], v211, s[80:81] offset:2048
	global_load_dwordx4 v[126:129], v210, s[74:75]
	s_and_saveexec_b64 s[2:3], s[8:9]
	s_waitcnt lgkmcnt(14)
	v_mfma_f32_32x32x16_bf16 v[2:17], v[130:133], v[186:189], v[2:17]
	v_add_f32_e32 v208, v62, v208
	v_add_f32_e32 v208, v63, v208
	v_exp_f32_e32 v66, v66
	v_exp_f32_e32 v67, v67
	s_waitcnt lgkmcnt(12)
	v_mfma_f32_32x32x16_bf16 v[2:17], v[134:137], v[190:193], v[2:17]
	v_add_f32_e32 v208, v64, v208
	v_add_f32_e32 v208, v65, v208
	v_add_f32_e32 v208, v34, v208
	v_exp_f32_e32 v68, v68
	v_exp_f32_e32 v69, v69
	s_waitcnt lgkmcnt(10)
	v_mfma_f32_32x32x16_bf16 v[2:17], v[138:141], v[194:197], v[2:17]
	v_add_f32_e32 v208, v35, v208
	v_add_f32_e32 v208, v36, v208
	v_add_f32_e32 v208, v37, v208
	v_exp_f32_e32 v70, v70
	v_exp_f32_e32 v71, v71
	s_waitcnt lgkmcnt(8)
	v_mfma_f32_32x32x16_bf16 v[2:17], v[142:145], v[198:201], v[2:17]
	v_add_f32_e32 v208, v38, v208
	v_add_f32_e32 v208, v39, v208
	v_exp_f32_e32 v72, v72
	v_exp_f32_e32 v73, v73
	s_waitcnt lgkmcnt(6)
	v_mfma_f32_32x32x16_bf16 v[18:33], v[130:133], v[222:225], v[18:33]
	v_add_f32_e32 v208, v40, v208
	v_add_f32_e32 v208, v41, v208
	v_exp_f32_e32 v74, v74
	v_exp_f32_e32 v75, v75
	s_waitcnt lgkmcnt(4)
	v_mfma_f32_32x32x16_bf16 v[18:33], v[134:137], v[226:229], v[18:33]
	v_add_f32_e32 v208, v42, v208
	v_add_f32_e32 v208, v43, v208
	v_add_f32_e32 v208, v44, v208
	v_exp_f32_e32 v76, v76
	v_exp_f32_e32 v77, v77
	s_waitcnt lgkmcnt(2)
	v_mfma_f32_32x32x16_bf16 v[18:33], v[138:141], v[230:233], v[18:33]
	v_add_f32_e32 v208, v45, v208
	v_add_f32_e32 v208, v46, v208
	v_add_f32_e32 v208, v47, v208
	v_exp_f32_e32 v78, v78
	v_exp_f32_e32 v79, v79
	s_waitcnt lgkmcnt(0)
	v_mfma_f32_32x32x16_bf16 v[18:33], v[142:145], v[234:237], v[18:33]
	v_add_f32_e32 v208, v48, v208
	v_add_f32_e32 v208, v49, v208
	v_exp_f32_e32 v80, v80
	v_exp_f32_e32 v81, v81
	v_add_f32_e32 v202, v202, v208
	s_branch .LBB0_842

; #define SBAR() __builtin_amdgcn_sched_barrier(0)
; #define SLOAD(i, key0) do { sr_[i].v = *reinterpret_cast<const bf16x8*>(&Vh[(long)((key0) + vr) * ldv + vc]); \
;     sr_[i].k0 = *reinterpret_cast<const bf16x8*>(&Kh[(long)((key0) + kr0) * ldk + kc0]); \
;     if (k2) sr_[i].k1 = *reinterpret_cast<const bf16x8*>(&Kh[(long)((key0) + kr1) * ldk + kc1]); } while (0)
; #define SWRITE(b, i) do { *(bf16x8*)((char*)V_lds + (b) * SHM_V + vst) = sr_[i].v; \
;     *(bf16x8*)((char*)K_lds + (b) * SHM_K + ksw0) = sr_[i].k0; \
;     if (k2) *(bf16x8*)((char*)K_lds + (b) * SHM_K + ksw1) = sr_[i].k1; } while (0)
; #define SWAIT() asm volatile("s_waitcnt vmcnt(2)" ::: "memory")
; #define RESC(a) do { if (__any((a) < 1.f)) { if (hi == 0) al_l[r32] = (a); asm volatile("s_waitcnt lgkmcnt(0)" ::: "memory"); \
;     _Pragma("unroll") for (int d = 0; d < 2; ++d) _Pragma("unroll") for (int r = 0; r < 16; ++r) o[d][r] *= al_l[crow(r, hi)]; } } while (0)
; template <int DQK>
; __device__ __forceinline__ void qkt(f32x16& p0, f32x16& p1, const bf16* Ks, const bf16x8* qr, int r32, int hi, int k0, int L) {
;   p0 = f32x16{}; p1 = f32x16{};
; #pragma unroll
;   for (int d0 = 0; d0 < DQK / 16; ++d0) { int cb = (d0 * 16 + hi * 8) * 2;
;     bf16x8 b0 = *reinterpret_cast<const bf16x8*>((const char*)Ks + KSWZ(r32, cb));
;     bf16x8 b1 = *reinterpret_cast<const bf16x8*>((const char*)Ks + KSWZ(32 + r32, cb));
;     p0 = __builtin_amdgcn_mfma_f32_32x32x16_bf16(b0, qr[d0], p0, 0, 0, 0);
;     p1 = __builtin_amdgcn_mfma_f32_32x32x16_bf16(b1, qr[d0], p1, 0, 0, 0); }
; template <int DQK, bool FIX>
; __device__ __forceinline__ void attn_item(const bf16* Qb, const bf16* __restrict__ Kh, const bf16* __restrict__ Vh,
;                                           u16* Ob, int q0, int L, int NT, char* lds, float mC) {
;     ...
;     __syncthreads(); SWAIT(); SWRITE(0, SE);
;     if (act) { RESC(alB); } __syncthreads();
;     if (act) { SBAR(); qkt<DQK>(pA0, pA1, K_lds, qr, r32, hi, (j + 1) * KVBLK, L);
;       finishSM(pB0, pB1, alB, l_reg, pa0, pa1, pa2, pa3); SBAR(); }
;     if (j + 3 < NT) SLOAD(SE, (j + 3) * KVBLK); SBAR();
.LBB0_842:
	s_or_b64 exec, exec, s[2:3]
	s_waitcnt lgkmcnt(0)
	s_barrier
	s_waitcnt vmcnt(2)
	s_waitcnt vmcnt(2)
	ds_write_b128 v160, v[114:117]
	ds_write_b128 v161, v[118:121] offset:49152
	s_and_saveexec_b64 s[2:3], s[8:9]
	s_cbranch_execz .LBB0_848
	s_add_i32 s6, s78, 0x80
	s_cmp_le_u32 s6, s79
	s_cbranch_scc0 .Lslow64b
	s_and_b64 vcc, exec, s[10:11]
	s_cbranch_vccz .Lslow64b
	ds_read_b128 v[222:225], v167 offset:32768
	ds_read_b128 v[226:229], v168 offset:32768
	ds_read_b128 v[230:233], v167 offset:40960
	ds_read_b128 v[234:237], v168 offset:40960
	ds_read_b128 v[238:241], v169 offset:32768
	ds_read_b128 v[242:245], v169 offset:40960
	ds_read_b128 v[246:249], v171 offset:32768
	ds_read_b128 v[250:253], v171 offset:40960
	v_cvt_pk_bf16_f32 v130, v66, v67
	v_cvt_pk_bf16_f32 v131, v68, v69
	v_cvt_pk_bf16_f32 v132, v70, v71
	v_cvt_pk_bf16_f32 v133, v72, v73
	v_cvt_pk_bf16_f32 v134, v74, v75
	v_cvt_pk_bf16_f32 v135, v76, v77
	v_cvt_pk_bf16_f32 v136, v78, v79
	v_cvt_pk_bf16_f32 v137, v80, v81
	s_waitcnt lgkmcnt(7)
	v_mfma_f32_32x32x16_bf16 v[50:65], v[222:225], v[98:101], 0
	ds_read_b64_tr_b16 v[186:187], v170 offset:0
	ds_read_b64_tr_b16 v[188:189], v170 offset:2048
	ds_read_b64_tr_b16 v[190:191], v170 offset:4096
	ds_read_b64_tr_b16 v[192:193], v170 offset:6144
	v_exp_f32_e32 v82, v82
	v_exp_f32_e32 v83, v83
	v_add_f32_e32 v208, 0, v66
	v_add_f32_e32 v208, v67, v208
	s_waitcnt lgkmcnt(10)
	v_mfma_f32_32x32x16_bf16 v[50:65], v[226:229], v[102:105], v[50:65]
	ds_read_b64_tr_b16 v[194:195], v170 offset:8192
	ds_read_b64_tr_b16 v[196:197], v170 offset:10240
	ds_read_b64_tr_b16 v[198:199], v170 offset:12288
	ds_read_b64_tr_b16 v[200:201], v170 offset:14336
	v_exp_f32_e32 v84, v84
	v_exp_f32_e32 v85, v85
	v_exp_f32_e32 v86, v86
	v_add_f32_e32 v208, v68, v208
	s_waitcnt lgkmcnt(13)
	v_mfma_f32_32x32x16_bf16 v[34:49], v[230:233], v[98:101], 0
	v_exp_f32_e32 v87, v87
	v_exp_f32_e32 v88, v88
	v_add_f32_e32 v208, v69, v208
	v_add_f32_e32 v208, v70, v208
	s_waitcnt lgkmcnt(12)
	v_mfma_f32_32x32x16_bf16 v[34:49], v[234:237], v[102:105], v[34:49]
	v_exp_f32_e32 v89, v89
	v_exp_f32_e32 v90, v90
	v_exp_f32_e32 v91, v91
	v_add_f32_e32 v208, v71, v208
	s_waitcnt lgkmcnt(11)
	v_mfma_f32_32x32x16_bf16 v[50:65], v[238:241], v[106:109], v[50:65]
	v_exp_f32_e32 v92, v92
	v_exp_f32_e32 v93, v93
	v_add_f32_e32 v208, v72, v208
	v_add_f32_e32 v208, v73, v208
	s_waitcnt lgkmcnt(10)
	v_mfma_f32_32x32x16_bf16 v[34:49], v[242:245], v[106:109], v[34:49]
	ds_read_b64_tr_b16 v[222:223], v170 offset:512
	ds_read_b64_tr_b16 v[224:225], v170 offset:2560
	ds_read_b64_tr_b16 v[226:227], v170 offset:4608
	ds_read_b64_tr_b16 v[228:229], v170 offset:6656
	v_exp_f32_e32 v94, v94
	v_exp_f32_e32 v95, v95
	v_exp_f32_e32 v96, v96
	v_add_f32_e32 v208, v74, v208
	s_waitcnt lgkmcnt(13)
	v_mfma_f32_32x32x16_bf16 v[50:65], v[246:249], v[110:113], v[50:65]
	v_exp_f32_e32 v97, v97
	v_cvt_pk_bf16_f32 v138, v82, v83
	v_cvt_pk_bf16_f32 v139, v84, v85
	v_cvt_pk_bf16_f32 v140, v86, v87
	v_add_f32_e32 v208, v75, v208
	s_waitcnt lgkmcnt(12)
	v_mfma_f32_32x32x16_bf16 v[34:49], v[250:253], v[110:113], v[34:49]
	ds_read_b64_tr_b16 v[230:231], v170 offset:8704
	ds_read_b64_tr_b16 v[232:233], v170 offset:10752
	ds_read_b64_tr_b16 v[234:235], v170 offset:12800
	s_waitcnt lgkmcnt(14)
	ds_read_b64_tr_b16 v[236:237], v170 offset:14848
	v_cvt_pk_bf16_f32 v141, v88, v89
	v_cvt_pk_bf16_f32 v142, v90, v91
	v_cvt_pk_bf16_f32 v143, v92, v93
	v_cvt_pk_bf16_f32 v144, v94, v95
	v_cvt_pk_bf16_f32 v145, v96, v97
	v_add_f32_e32 v208, v76, v208
	v_add_f32_e32 v208, v77, v208
	s_or_b64 exec, exec, s[2:3]
	s_cmp_ge_u32 s73, s97
	s_cselect_b64 s[2:3], -1, 0
	s_and_b64 vcc, exec, s[2:3]
	s_cbranch_vccnz .Lfast64b_nl
	global_load_dwordx4 v[114:117], v211, s[84:85] offset:2048
	global_load_dwordx4 v[118:121], v210, s[76:77]

; #define SBAR() __builtin_amdgcn_sched_barrier(0)
; #define SLOAD(i, key0) do { sr_[i].v = *reinterpret_cast<const bf16x8*>(&Vh[(long)((key0) + vr) * ldv + vc]); \
;     sr_[i].k0 = *reinterpret_cast<const bf16x8*>(&Kh[(long)((key0) + kr0) * ldk + kc0]); \
;     if (k2) sr_[i].k1 = *reinterpret_cast<const bf16x8*>(&Kh[(long)((key0) + kr1) * ldk + kc1]); } while (0)
; template <int DQK, bool FIX>
; __device__ __forceinline__ void attn_item(const bf16* Qb, const bf16* __restrict__ Kh, const bf16* __restrict__ Vh,
;                                           u16* Ob, int q0, int L, int NT, char* lds, float mC) {
;     ...
;     if (act) { SBAR(); qkt<DQK>(pA0, pA1, K_lds, qr, r32, hi, (j + 1) * KVBLK, L);
;       finishSM(pB0, pB1, alB, l_reg, pa0, pa1, pa2, pa3); SBAR(); }
;     if (j + 3 < NT) SLOAD(SE, (j + 3) * KVBLK); SBAR();
.LBB0_848:
	s_or_b64 exec, exec, s[2:3]
	s_cmp_ge_u32 s73, s97
	s_cselect_b64 s[2:3], -1, 0
	s_and_b64 vcc, exec, s[2:3]
	s_cbranch_vccnz .LBB0_850
	v_lshl_add_u64 v[152:153], v[148:149], 0, s[4:5]
	v_lshl_add_u64 v[150:151], v[146:147], 0, s[4:5]
	v_add_co_u32_e32 v114, vcc, 0x2ced4000, v152
	s_nop 1
	v_addc_co_u32_e32 v115, vcc, 0, v153, vcc
	v_add_co_u32_e32 v118, vcc, 0x119d4000, v150
	global_load_dwordx4 v[114:117], v[114:115], off offset:2048
	s_nop 0
	v_addc_co_u32_e32 v119, vcc, 0, v151, vcc
	global_load_dwordx4 v[118:121], v[118:119], off

; __device__ __forceinline__ void finishSM(f32x16& p0, f32x16& p1, float alpha, float& l_reg, bf16x8& pa0, bf16x8& pa1, bf16x8& pa2, bf16x8& pa3) {
; #pragma unroll
;   for (int r = 0; r < 16; ++r) p1[r] = __builtin_amdgcn_exp2f(p1[r]);
;   float ps = 0;
; #pragma unroll
;   for (int r = 0; r < 16; ++r) ps += p0[r];
; #pragma unroll
;   for (int r = 0; r < 16; ++r) ps += p1[r];
;   { auto rr = __builtin_amdgcn_permlane32_swap(__float_as_uint(ps), __float_as_uint(ps), false, false);
;     ps = __uint_as_float(rr[0]) + __uint_as_float(rr[1]); }
;   l_reg = l_reg * alpha + ps;
;     ...
;   PK4(p0, 0, pa0); PK4(p0, 8, pa1); PK4(p1, 0, pa2); PK4(p1, 8, pa3);
;     ...
; }
; template <int DQK>
; __device__ __forceinline__ void qkt(f32x16& p0, f32x16& p1, const bf16* Ks, const bf16x8* qr, int r32, int hi, int k0, int L) {
;   p0 = f32x16{}; p1 = f32x16{};
; #pragma unroll
;   for (int d0 = 0; d0 < DQK / 16; ++d0) { int cb = (d0 * 16 + hi * 8) * 2;
;     bf16x8 b0 = *reinterpret_cast<const bf16x8*>((const char*)Ks + KSWZ(r32, cb));
;     bf16x8 b1 = *reinterpret_cast<const bf16x8*>((const char*)Ks + KSWZ(32 + r32, cb));
;     p0 = __builtin_amdgcn_mfma_f32_32x32x16_bf16(b0, qr[d0], p0, 0, 0, 0);
;     p1 = __builtin_amdgcn_mfma_f32_32x32x16_bf16(b1, qr[d0], p1, 0, 0, 0); }
;   if (k0 + KVBLK > L) {
; #pragma unroll
;     for (int r = 0; r < 16; ++r) { const int key = k0 + crow(r, hi);
;       if (key >= L) p0[r] = -1e30f;
;       if (key + 32 >= L) p1[r] = -1e30f; }
;   }
; }
; __device__ __forceinline__ int v_st(int k, int c) { const int kk = (k & ~0xC) | ((k & 4) << 1) | ((k & 8) >> 1); return ((kk >> 3) * 4 + (c >> 5)) * 512 + ((kk & 7) * 32 + (c & 31)) * 2; }
; __device__ __forceinline__ int v_rd_base(int lane) { return ((lane & 3) << 3) | (((lane >> 2) & 3) << 6) | (((lane >> 4) & 1) << 5) | (((lane >> 5) & 1) << 8); }
; template <int OFF> __device__ __forceinline__ s16x4 tr_read(int vb) {
;   s16x4 r; asm volatile("ds_read_b64_tr_b16 %0, %1 offset:%2" : "=&v"(r) : "v"(vb), "i"(OFF) : "memory"); return r;
; template <int DQK, bool FIX>
; __device__ __forceinline__ void attn_item(const bf16* Qb, const bf16* __restrict__ Kh, const bf16* __restrict__ Vh,
;                                           u16* Ob, int q0, int L, int NT, char* lds, float mC) {
;     ...
;   if (NT & 1) {
;     if (act) { finishSM(pA0, pA1, alA, l_reg, pa0, pa1, pa2, pa3); SBAR(); pv_d0(o, vb0, pa0, pa1, pa2, pa3); }
.LBB0_853:
	s_mov_b64 s[74:75], 0x2149c980
	s_mov_b64 s[76:77], 0x21544900
	s_mov_b64 s[80:81], 0x14200180
	s_mov_b64 s[84:85], 0x14200100
	s_and_saveexec_b64 s[2:3], s[8:9]
	v_readlane_b32 s6, v254, 61
	s_cbranch_execz .LBB0_855
	v_mov_b32_e32 v203, v202
	s_nop 1
	v_permlane32_swap_b32_e32 v202, v203
	v_add_f32_e32 v202, v202, v203
	v_add_f32_e32 v163, v163, v202
	v_exp_f32_e32 v66, v34
	v_add_f32_e32 v34, 0, v50
	v_add_f32_e32 v34, v51, v34
	v_add_f32_e32 v34, v52, v34
	v_add_f32_e32 v34, v53, v34
	v_add_f32_e32 v34, v54, v34
	v_add_f32_e32 v34, v55, v34
	v_add_f32_e32 v34, v56, v34
	v_add_f32_e32 v34, v57, v34
	v_add_f32_e32 v34, v58, v34
	v_add_f32_e32 v34, v59, v34
	v_add_f32_e32 v34, v60, v34
	v_add_f32_e32 v34, v61, v34
	v_add_f32_e32 v34, v62, v34
	v_exp_f32_e32 v67, v35
	v_add_f32_e32 v34, v63, v34
	v_exp_f32_e32 v68, v36
	v_add_f32_e32 v34, v64, v34
	v_exp_f32_e32 v69, v37
	v_add_f32_e32 v34, v65, v34
	v_exp_f32_e32 v70, v38
	v_add_f32_e32 v34, v66, v34
	v_exp_f32_e32 v71, v39
	v_add_f32_e32 v34, v67, v34
	v_exp_f32_e32 v72, v40
	v_add_f32_e32 v34, v68, v34
	v_exp_f32_e32 v73, v41
	v_add_f32_e32 v34, v69, v34
	v_exp_f32_e32 v74, v42
	v_add_f32_e32 v34, v70, v34
	v_exp_f32_e32 v75, v43
	v_add_f32_e32 v34, v71, v34
	v_exp_f32_e32 v76, v44
	v_add_f32_e32 v34, v72, v34
	v_exp_f32_e32 v77, v45
	v_add_f32_e32 v34, v73, v34
	v_exp_f32_e32 v78, v46
	v_add_f32_e32 v34, v74, v34
	v_exp_f32_e32 v79, v47
	v_add_f32_e32 v34, v75, v34
	v_exp_f32_e32 v80, v48
	v_add_f32_e32 v34, v76, v34
	v_exp_f32_e32 v49, v49
	v_add_f32_e32 v34, v77, v34
	v_add_f32_e32 v34, v78, v34
	v_add_f32_e32 v34, v79, v34
	v_add_f32_e32 v34, v80, v34
	v_add_f32_e32 v34, v49, v34
	v_mov_b32_e32 v35, v34
	s_nop 1
	v_permlane32_swap_b32_e32 v34, v35
	v_add_f32_e32 v34, v34, v35
	v_add_f32_e32 v163, v163, v34
	v_cvt_pk_bf16_f32 v34, v50, v51
	v_cvt_pk_bf16_f32 v35, v52, v53
	v_cvt_pk_bf16_f32 v36, v54, v55
	v_cvt_pk_bf16_f32 v37, v56, v57
	v_cvt_pk_bf16_f32 v38, v58, v59
	v_cvt_pk_bf16_f32 v39, v60, v61
	v_cvt_pk_bf16_f32 v40, v62, v63
	v_cvt_pk_bf16_f32 v41, v64, v65
	v_cvt_pk_bf16_f32 v42, v66, v67
	v_cvt_pk_bf16_f32 v43, v68, v69
	v_cvt_pk_bf16_f32 v44, v70, v71
	v_cvt_pk_bf16_f32 v45, v72, v73
	v_cvt_pk_bf16_f32 v46, v74, v75
	v_cvt_pk_bf16_f32 v47, v76, v77
	v_cvt_pk_bf16_f32 v48, v78, v79
	v_cvt_pk_bf16_f32 v49, v80, v49
	ds_read_b64_tr_b16 v[50:51], v166 offset:0
	ds_read_b64_tr_b16 v[52:53], v166 offset:0x800
	ds_read_b64_tr_b16 v[54:55], v166 offset:0x1000
	ds_read_b64_tr_b16 v[56:57], v166 offset:0x1800
	ds_read_b64_tr_b16 v[58:59], v166 offset:0x2000
	ds_read_b64_tr_b16 v[60:61], v166 offset:0x2800
	ds_read_b64_tr_b16 v[62:63], v166 offset:0x3000
	ds_read_b64_tr_b16 v[64:65], v166 offset:0x3800
	s_waitcnt lgkmcnt(0)
	s_nop 0
	v_mfma_f32_32x32x16_bf16 v[2:17], v[34:37], v[50:53], v[2:17]
	ds_read_b64_tr_b16 v[50:51], v166 offset:0x200
	ds_read_b64_tr_b16 v[52:53], v166 offset:0xa00
	v_mfma_f32_32x32x16_bf16 v[2:17], v[38:41], v[54:57], v[2:17]
	ds_read_b64_tr_b16 v[54:55], v166 offset:0x1200
	ds_read_b64_tr_b16 v[56:57], v166 offset:0x1a00
	v_mfma_f32_32x32x16_bf16 v[2:17], v[42:45], v[58:61], v[2:17]
	ds_read_b64_tr_b16 v[58:59], v166 offset:0x2200
	ds_read_b64_tr_b16 v[60:61], v166 offset:0x2a00
	v_mfma_f32_32x32x16_bf16 v[2:17], v[46:49], v[62:65], v[2:17]
	ds_read_b64_tr_b16 v[62:63], v166 offset:0x3200
	ds_read_b64_tr_b16 v[64:65], v166 offset:0x3a00
	s_waitcnt lgkmcnt(0)
	v_mfma_f32_32x32x16_bf16 v[18:33], v[34:37], v[50:53], v[18:33]
	v_mfma_f32_32x32x16_bf16 v[18:33], v[38:41], v[54:57], v[18:33]
	v_mfma_f32_32x32x16_bf16 v[18:33], v[42:45], v[58:61], v[18:33]
	v_mfma_f32_32x32x16_bf16 v[18:33], v[46:49], v[62:65], v[18:33]

; __device__ __forceinline__ int v_st(int k, int c) { const int kk = (k & ~0xC) | ((k & 4) << 1) | ((k & 8) >> 1); return ((kk >> 3) * 4 + (c >> 5)) * 512 + ((kk & 7) * 32 + (c & 31)) * 2; }
; __device__ __forceinline__ int v_rd_base(int lane) { return ((lane & 3) << 3) | (((lane >> 2) & 3) << 6) | (((lane >> 4) & 1) << 5) | (((lane >> 5) & 1) << 8); }
; #define SLOAD(i, key0) do { sr_[i].v = *reinterpret_cast<const bf16x8*>(&Vh[(long)((key0) + vr) * ldv + vc]); \
;     sr_[i].k0 = *reinterpret_cast<const bf16x8*>(&Kh[(long)((key0) + kr0) * ldk + kc0]); \
;     if (k2) sr_[i].k1 = *reinterpret_cast<const bf16x8*>(&Kh[(long)((key0) + kr1) * ldk + kc1]); } while (0)
; #define SWRITE(b, i) do { *(bf16x8*)((char*)V_lds + (b) * SHM_V + vst) = sr_[i].v; \
;     *(bf16x8*)((char*)K_lds + (b) * SHM_K + ksw0) = sr_[i].k0; \
;     if (k2) *(bf16x8*)((char*)K_lds + (b) * SHM_K + ksw1) = sr_[i].k1; } while (0)
; template <int DQK, bool FIX>
; __device__ __forceinline__ void attn_item(const bf16* Qb, const bf16* __restrict__ Kh, const bf16* __restrict__ Vh,
;                                           u16* Ob, int q0, int L, int NT, char* lds, float mC) {
;     ...
;   float m_reg = -1e30f, l_reg = 0; f32x16 o[2] = {}; bf16x8 qr[ND];
;   __syncthreads();
;   { int qrow = q0 + wid * 32 + r32; if (qrow > L - 1) qrow = L - 1;
;     const bf16* Qw = Qb + (long)qrow * ldq + hi * 8;
; #pragma unroll
;     for (int d0 = 0; d0 < ND; ++d0) qr[d0] = *reinterpret_cast<const bf16x8*>(Qw + d0 * 16); }
;   const int vr = tid >> 3, vc = (tid & 7) * 8, vst = v_st(vr, vc);
;   const int kr0 = tid / KCH, kc0 = (tid % KCH) * 8, kr1 = (tid + 512) / KCH, kc1 = ((tid + 512) % KCH) * 8;
;   const bool k2 = (DQK == 96) && (tid < 256);
;   const int ksw0 = KSWZ(kr0, kc0 * 2), ksw1 = KSWZ(kr1, kc1 * 2);
;   const int vb0 = (int)(uintptr_t)V_lds + v_rd_base(lane);
;   struct { bf16x8 v, k0, k1; } sr_[2];
;     ...
;   f32x16 pA0, pA1, pB0, pB1; float mnA = 0.f, mnB = 0.f, alA = 1.f, alB = 1.f; bf16x8 pa0, pa1, pa2, pa3;
;   constexpr int SE = 0, SO = 1;
;   const bool act = (q0 + wid * 32) < L;
;   SLOAD(SE, 0); asm volatile("s_waitcnt vmcnt(0)" ::: "memory"); SWRITE(0, SE); __syncthreads();
;   if (act) { qkt<DQK>(pA0, pA1, K_lds, qr, r32, hi, 0, L); partialSM<DQK, FIX>(pA0, pA1, m_reg, mnA, alA, mC); }
;   SLOAD(SO, KVBLK); if (2 < NT) SLOAD(SE, 2 * KVBLK);
;   SWAIT(); SWRITE(1, SO); __syncthreads();
.LBB0_879:
	s_or_b64 exec, exec, s[6:7]
	s_waitcnt vmcnt(2)
	s_waitcnt vmcnt(3)
	ds_write_b128 v193, v[2:5] offset:16384
	s_waitcnt vmcnt(2)
	ds_write_b128 v194, v[6:9] offset:49152
	s_and_saveexec_b64 s[2:3], s[8:9]
	ds_write_b128 v195, v[140:143] offset:49152
	s_or_b64 exec, exec, s[2:3]
	v_lshlrev_b32_e32 v3, 4, v192
	v_lshlrev_b32_e32 v2, 3, v192
	v_and_b32_e32 v3, 0xc0, v3
	v_lshlrev_b32_e32 v4, 1, v192
	v_and_or_b32 v3, v2, 24, v3
	v_and_b32_e32 v4, 32, v4
	v_and_b32_e32 v2, 0x100, v2
	s_cmp_lg_u32 0, -1
	v_or3_b32 v2, v3, v4, v2
	s_cselect_b32 s2, 0, 0
	v_add_u32_e32 v197, s2, v2
	s_addk_i32 s2, 0x4000
	s_lshr_b32 s16, s19, 1
	v_and_b32_e32 v3, 0xf0, v31
	v_or_b32_e32 v4, 32, v0
	v_add_u32_e32 v199, s2, v2
	s_mul_i32 s2, s16, 0xc0
	s_mul_i32 s3, s18, 0x60
	v_xad_u32 v17, v4, v3, 0
	v_or_b32_e32 v4, 64, v0
	s_add_i32 s2, s2, s3
	v_xad_u32 v24, v4, v3, 0
	v_or_b32_e32 v4, 0x60, v0
	s_ashr_i32 s3, s2, 31
	v_xad_u32 v16, v0, v3, 0
	v_xad_u32 v25, v4, v3, 0
	v_or_b32_e32 v4, 0x80, v0
	v_or_b32_e32 v0, 0xa0, v0
	s_lshl_b64 s[6:7], s[2:3], 1
	s_mul_hi_u32 s2, s82, 0x600
	s_mul_i32 s3, s82, 0x600
	v_xad_u32 v26, v4, v3, 0
	v_xad_u32 v27, v0, v3, 0
	v_mov_b32_e32 v2, s3
	v_mov_b32_e32 v3, s2
	v_mad_i64_i32 v[2:3], s[2:3], v28, s65, v[2:3]
	v_readlane_b32 s20, v254, 35
	v_lshl_add_u64 v[2:3], v[22:23], 1, v[2:3]
	v_readlane_b32 s21, v254, 36
	s_sub_i32 s5, s96, 64
	s_sub_i32 s78, s96, 32
	v_lshl_add_u64 v[166:167], s[20:21], 0, v[2:3]
	v_mad_u64_u32 v[2:3], s[2:3], s82, v185, v[10:11]
	s_lshl_b32 s2, s16, 7
	s_lshl_b32 s3, s18, 6
	s_add_i32 s2, s2, s3
	v_lshl_add_u64 v[2:3], v[18:19], 1, v[2:3]
	s_ashr_i32 s3, s2, 31
	v_lshl_add_u64 v[168:169], s[20:21], 0, v[2:3]
	v_lshl_add_u64 v[2:3], v[20:21], 0, s[14:15]
	v_and_b32_e32 v0, 7, v176
	s_lshl_b64 s[2:3], s[2:3], 1
	v_readlane_b32 s14, v254, 57
	v_lshlrev_b32_e32 v0, 4, v0
	s_add_u32 s2, s14, s2
	v_readlane_b32 s14, v254, 58
	v_lshl_add_u64 v[2:3], v[2:3], 0, v[0:1]
	s_addc_u32 s3, s14, s3
	v_mov_b32_e32 v14, v1
	v_mov_b32_e32 v15, v1
	v_lshl_add_u64 v[170:171], s[2:3], 0, v[2:3]
	v_mov_b32_e32 v0, v1
	v_mov_b32_e32 v2, v1
	v_mov_b32_e32 v3, v1
	v_mov_b32_e32 v4, v1
	v_mov_b32_e32 v5, v1
	v_mov_b32_e32 v6, v1
	v_mov_b32_e32 v7, v1
	v_mov_b32_e32 v8, v1
	v_mov_b32_e32 v9, v1
	v_mov_b32_e32 v10, v1
	v_mov_b32_e32 v11, v1
	v_mov_b32_e32 v12, v1
	v_mov_b32_e32 v13, v1
	v_add_u32_e32 v200, v16, v29
	v_add_u32_e32 v201, v17, v29
	v_add_u32_e32 v202, v24, v29
	v_add_u32_e32 v203, v25, v29
	v_add_u32_e32 v204, v26, v29
	v_add_u32_e32 v205, v27, v29
	v_mov_b64_e32 v[46:47], v[14:15]
	v_mov_b64_e32 v[30:31], v[14:15]
	v_mov_b64_e32 v[94:95], v[14:15]
	v_mov_b64_e32 v[110:111], v[14:15]
	s_mov_b32 s79, 4
	s_mov_b32 s4, 0
	v_lshlrev_b32_e32 v196, 2, v189
	v_mov_b32_e32 v198, 0
	v_mov_b64_e32 v[44:45], v[12:13]
	v_mov_b64_e32 v[42:43], v[10:11]
	v_mov_b64_e32 v[40:41], v[8:9]
	v_mov_b64_e32 v[38:39], v[6:7]
	v_mov_b64_e32 v[36:37], v[4:5]
	v_mov_b64_e32 v[34:35], v[2:3]
	v_mov_b64_e32 v[32:33], v[0:1]
	v_mov_b64_e32 v[28:29], v[12:13]
	v_mov_b64_e32 v[26:27], v[10:11]
	v_mov_b64_e32 v[24:25], v[8:9]
	v_mov_b64_e32 v[22:23], v[6:7]
	v_mov_b64_e32 v[20:21], v[4:5]
	v_mov_b64_e32 v[18:19], v[2:3]
	v_mov_b64_e32 v[16:17], v[0:1]
	v_mov_b64_e32 v[92:93], v[12:13]
	v_mov_b64_e32 v[90:91], v[10:11]
	v_mov_b64_e32 v[88:89], v[8:9]
	v_mov_b64_e32 v[86:87], v[6:7]
	v_mov_b64_e32 v[84:85], v[4:5]
	v_mov_b64_e32 v[82:83], v[2:3]
	v_mov_b64_e32 v[80:81], v[0:1]
	v_mov_b64_e32 v[108:109], v[12:13]
	v_mov_b64_e32 v[106:107], v[10:11]
	v_mov_b64_e32 v[104:105], v[8:9]
	v_mov_b64_e32 v[102:103], v[6:7]
	v_mov_b64_e32 v[100:101], v[4:5]
	v_mov_b64_e32 v[98:99], v[2:3]
	v_mov_b64_e32 v[96:97], v[0:1]
	s_waitcnt lgkmcnt(0)
	s_barrier
	s_waitcnt vmcnt(1)
	ds_write_b128 v194, v[222:225] offset:32768
	s_and_saveexec_b64 s[2:3], s[8:9]
	ds_write_b128 v195, v[226:229] offset:32768
	s_or_b64 exec, exec, s[2:3]
	v_readlane_b32 s22, v254, 37
	v_readlane_b32 s23, v254, 38
	v_mov_b32_e32 v186, 0
	v_readfirstlane_b32 s74, v168
	v_readfirstlane_b32 s75, v169
	v_readfirstlane_b32 s84, v170
	v_readfirstlane_b32 s85, v171
	s_nop 3
	v_subrev_u32_e32 v15, s74, v168
	v_subrev_u32_e32 v188, s74, v166
	v_subrev_u32_e32 v14, s84, v170
	s_add_u32 s74, s74, s6
	s_addc_u32 s75, s75, s7
	s_add_u32 s74, s74, 0xa160000
	s_addc_u32 s75, s75, 0
	s_add_u32 s76, s74, 0x18000
	s_addc_u32 s77, s75, 0
	s_sub_u32 s80, s84, 0x10000
	s_subb_u32 s81, s85, 0
	s_branch .LBB0_883
; #define SBAR() __builtin_amdgcn_sched_barrier(0)
; #define SLOAD(i, key0) do { sr_[i].v = *reinterpret_cast<const bf16x8*>(&Vh[(long)((key0) + vr) * ldv + vc]); \
;     sr_[i].k0 = *reinterpret_cast<const bf16x8*>(&Kh[(long)((key0) + kr0) * ldk + kc0]); \
;     if (k2) sr_[i].k1 = *reinterpret_cast<const bf16x8*>(&Kh[(long)((key0) + kr1) * ldk + kc1]); } while (0)
; template <int DQK>
; __device__ __forceinline__ void qkt(f32x16& p0, f32x16& p1, const bf16* Ks, const bf16x8* qr, int r32, int hi, int k0, int L) {
;   p0 = f32x16{}; p1 = f32x16{};
; #pragma unroll
;   for (int d0 = 0; d0 < DQK / 16; ++d0) { int cb = (d0 * 16 + hi * 8) * 2;
;     bf16x8 b0 = *reinterpret_cast<const bf16x8*>((const char*)Ks + KSWZ(r32, cb));
;     bf16x8 b1 = *reinterpret_cast<const bf16x8*>((const char*)Ks + KSWZ(32 + r32, cb));
;     p0 = __builtin_amdgcn_mfma_f32_32x32x16_bf16(b0, qr[d0], p0, 0, 0, 0);
;     p1 = __builtin_amdgcn_mfma_f32_32x32x16_bf16(b1, qr[d0], p1, 0, 0, 0); }
; template <int DQK, bool FIX>
; __device__ __forceinline__ void attn_item(const bf16* Qb, const bf16* __restrict__ Kh, const bf16* __restrict__ Vh,
;                                           u16* Ob, int q0, int L, int NT, char* lds, float mC) {
;     ...
;   for (int j = 1; j + 1 < NT; j += 2) {
;     if (act) { SBAR(); qkt<DQK>(pB0, pB1, (bf16*)((char*)K_lds + SHM_K), qr, r32, hi, j * KVBLK, L);
;       finishSM(pA0, pA1, alA, l_reg, pa0, pa1, pa2, pa3); SBAR(); }
;     SLOAD(SO, (j + 2) * KVBLK); SBAR();
;     if (act) { pv_d0(o, vb0, pa0, pa1, pa2, pa3); partialSM<DQK, FIX>(pB0, pB1, m_reg, mnB, alB, mC); }
.LBB0_882:
	s_or_b64 exec, exec, s[14:15]
	s_mov_b64 s[14:15], 0x30000
	v_lshl_add_u64 v[166:167], v[166:167], 0, s[14:15]
	v_lshl_add_u64 v[168:169], v[168:169], 0, s[14:15]
	s_mov_b64 s[14:15], 0x20000
	s_addk_i32 s4, 0x80
	v_lshl_add_u64 v[170:171], v[170:171], 0, s[14:15]
	s_add_i32 s79, s79, 2
	s_add_u32 s74, s74, 0x30000
	s_addc_u32 s75, s75, 0
	s_add_u32 s76, s76, 0x30000
	s_addc_u32 s77, s77, 0
	s_add_u32 s80, s80, 0x20000
	s_addc_u32 s81, s81, 0
	s_add_u32 s84, s84, 0x20000
	s_addc_u32 s85, s85, 0
	s_and_b64 vcc, exec, s[2:3]
	s_cbranch_vccnz .LBB0_913
.LBB0_883:
	s_and_saveexec_b64 s[2:3], s[10:11]
	s_cbranch_execz .LBB0_889
	s_add_i32 s14, s4, 64
	s_cmp_le_u32 s14, s5
	s_cbranch_scc0 .Lslow96a
	s_and_b64 vcc, exec, s[12:13]
	s_cbranch_vccz .Lslow96a
	ds_read_b128 v[222:225], v200 offset:49152
	ds_read_b128 v[226:229], v200 offset:57344
	ds_read_b128 v[230:233], v201 offset:49152
	ds_read_b128 v[234:237], v201 offset:57344
	ds_read_b128 v[238:241], v202 offset:49152
	ds_read_b128 v[242:245], v202 offset:57344
	ds_read_b128 v[246:249], v203 offset:49152
	ds_read_b128 v[250:253], v203 offset:57344
	v_cvt_pk_bf16_f32 v10, v64, v65
	v_cvt_pk_bf16_f32 v11, v66, v67
	v_cvt_pk_bf16_f32 v12, v68, v69
	v_cvt_pk_bf16_f32 v13, v70, v71
	v_cvt_pk_bf16_f32 v152, v72, v73
	v_cvt_pk_bf16_f32 v153, v74, v75
	v_cvt_pk_bf16_f32 v154, v76, v77
	v_cvt_pk_bf16_f32 v155, v78, v79
	s_waitcnt lgkmcnt(7)
	v_mfma_f32_32x32x16_bf16 v[80:95], v[222:225], v[112:115], 0
	ds_read_b128 v[222:225], v204 offset:49152
	ds_read_b64_tr_b16 v[206:207], v197 offset:0
	ds_read_b64_tr_b16 v[208:209], v197 offset:2048
	ds_read_b64_tr_b16 v[210:211], v197 offset:4096
	ds_read_b64_tr_b16 v[212:213], v197 offset:6144
	v_exp_f32_e32 v48, v48
	v_exp_f32_e32 v49, v49
	v_add_f32_e32 v0, 0, v64
	s_waitcnt lgkmcnt(11)
	v_mfma_f32_32x32x16_bf16 v[96:111], v[226:229], v[112:115], 0
	ds_read_b128 v[226:229], v204 offset:57344
	ds_read_b64_tr_b16 v[214:215], v197 offset:8192
	ds_read_b64_tr_b16 v[216:217], v197 offset:10240
	ds_read_b64_tr_b16 v[218:219], v197 offset:12288
	s_waitcnt lgkmcnt(14)
	ds_read_b64_tr_b16 v[220:221], v197 offset:14336
	v_exp_f32_e32 v50, v50
	v_exp_f32_e32 v51, v51
	v_add_f32_e32 v0, v65, v0
	v_mfma_f32_32x32x16_bf16 v[80:95], v[230:233], v[116:119], v[80:95]
	s_waitcnt lgkmcnt(14)
	ds_read_b128 v[230:233], v205 offset:49152
	v_exp_f32_e32 v52, v52
	v_exp_f32_e32 v53, v53
	v_add_f32_e32 v0, v66, v0
	v_mfma_f32_32x32x16_bf16 v[96:111], v[234:237], v[116:119], v[96:111]
	s_waitcnt lgkmcnt(14)
	ds_read_b128 v[234:237], v205 offset:57344
	v_exp_f32_e32 v54, v54
	v_exp_f32_e32 v55, v55
	v_add_f32_e32 v0, v67, v0
	v_mfma_f32_32x32x16_bf16 v[80:95], v[238:241], v[120:123], v[80:95]
	v_exp_f32_e32 v56, v56
	v_exp_f32_e32 v57, v57
	v_add_f32_e32 v0, v68, v0
	s_waitcnt lgkmcnt(14)
	v_mfma_f32_32x32x16_bf16 v[96:111], v[242:245], v[120:123], v[96:111]
	v_exp_f32_e32 v58, v58
	v_exp_f32_e32 v59, v59
	v_add_f32_e32 v0, v69, v0
	s_waitcnt lgkmcnt(13)
	v_mfma_f32_32x32x16_bf16 v[80:95], v[246:249], v[124:127], v[80:95]
	v_exp_f32_e32 v60, v60
	v_exp_f32_e32 v61, v61
	v_add_f32_e32 v0, v70, v0
	s_waitcnt lgkmcnt(12)
	v_mfma_f32_32x32x16_bf16 v[96:111], v[250:253], v[124:127], v[96:111]
	v_exp_f32_e32 v62, v62
	v_exp_f32_e32 v63, v63
	v_add_f32_e32 v0, v71, v0
	s_waitcnt lgkmcnt(11)
	v_mfma_f32_32x32x16_bf16 v[80:95], v[222:225], v[128:131], v[80:95]
	ds_read_b64_tr_b16 v[238:239], v197 offset:512
	ds_read_b64_tr_b16 v[240:241], v197 offset:2560
	ds_read_b64_tr_b16 v[242:243], v197 offset:4608
	ds_read_b64_tr_b16 v[244:245], v197 offset:6656
	v_cvt_pk_bf16_f32 v156, v48, v49
	v_cvt_pk_bf16_f32 v157, v50, v51
	v_cvt_pk_bf16_f32 v158, v52, v53
	v_cvt_pk_bf16_f32 v159, v54, v55
	v_add_f32_e32 v0, v72, v0
	v_add_f32_e32 v0, v73, v0
	s_waitcnt lgkmcnt(10)
	v_mfma_f32_32x32x16_bf16 v[96:111], v[226:229], v[128:131], v[96:111]
	v_cvt_pk_bf16_f32 v160, v56, v57
	v_cvt_pk_bf16_f32 v161, v58, v59
	v_cvt_pk_bf16_f32 v162, v60, v61
	v_cvt_pk_bf16_f32 v163, v62, v63
	v_add_f32_e32 v0, v74, v0
	v_add_f32_e32 v0, v75, v0
	s_waitcnt lgkmcnt(5)
	v_mfma_f32_32x32x16_bf16 v[80:95], v[230:233], v[132:135], v[80:95]
	ds_read_b64_tr_b16 v[246:247], v197 offset:8704
	ds_read_b64_tr_b16 v[248:249], v197 offset:10752
	ds_read_b64_tr_b16 v[250:251], v197 offset:12800
	ds_read_b64_tr_b16 v[252:253], v197 offset:14848
	v_add_f32_e32 v0, v76, v0
	v_add_f32_e32 v0, v77, v0
	v_add_f32_e32 v0, v78, v0
	v_add_f32_e32 v0, v79, v0
	v_add_f32_e32 v0, v48, v0
	s_waitcnt lgkmcnt(8)
	v_mfma_f32_32x32x16_bf16 v[96:111], v[234:237], v[132:135], v[96:111]
	v_add_f32_e32 v0, v49, v0
	v_add_f32_e32 v0, v50, v0
	v_add_f32_e32 v0, v51, v0
	v_add_f32_e32 v0, v52, v0
	v_add_f32_e32 v0, v53, v0
	s_or_b64 exec, exec, s[2:3]
	global_load_dwordx4 v[2:5], v14, s[80:81]
	global_load_dwordx4 v[6:9], v15, s[74:75]
	s_and_saveexec_b64 s[2:3], s[8:9]
	s_cbranch_execz .Lfast96a_k2
	global_load_dwordx4 v[140:143], v188, s[74:75]

; #define SBAR() __builtin_amdgcn_sched_barrier(0)
; #define SLOAD(i, key0) do { sr_[i].v = *reinterpret_cast<const bf16x8*>(&Vh[(long)((key0) + vr) * ldv + vc]); \
;     sr_[i].k0 = *reinterpret_cast<const bf16x8*>(&Kh[(long)((key0) + kr0) * ldk + kc0]); \
;     if (k2) sr_[i].k1 = *reinterpret_cast<const bf16x8*>(&Kh[(long)((key0) + kr1) * ldk + kc1]); } while (0)
; #define SWRITE(b, i) do { *(bf16x8*)((char*)V_lds + (b) * SHM_V + vst) = sr_[i].v; \
;     *(bf16x8*)((char*)K_lds + (b) * SHM_K + ksw0) = sr_[i].k0; \
;     if (k2) *(bf16x8*)((char*)K_lds + (b) * SHM_K + ksw1) = sr_[i].k1; } while (0)
; #define SWAIT() asm volatile("s_waitcnt vmcnt(2)" ::: "memory")
; #define RESC(a) do { if (__any((a) < 1.f)) { if (hi == 0) al_l[r32] = (a); asm volatile("s_waitcnt lgkmcnt(0)" ::: "memory"); \
;     _Pragma("unroll") for (int d = 0; d < 2; ++d) _Pragma("unroll") for (int r = 0; r < 16; ++r) o[d][r] *= al_l[crow(r, hi)]; } } while (0)
; template <int DQK>
; __device__ __forceinline__ void qkt(f32x16& p0, f32x16& p1, const bf16* Ks, const bf16x8* qr, int r32, int hi, int k0, int L) {
;   p0 = f32x16{}; p1 = f32x16{};
; #pragma unroll
;   for (int d0 = 0; d0 < DQK / 16; ++d0) { int cb = (d0 * 16 + hi * 8) * 2;
;     bf16x8 b0 = *reinterpret_cast<const bf16x8*>((const char*)Ks + KSWZ(r32, cb));
;     bf16x8 b1 = *reinterpret_cast<const bf16x8*>((const char*)Ks + KSWZ(32 + r32, cb));
;     p0 = __builtin_amdgcn_mfma_f32_32x32x16_bf16(b0, qr[d0], p0, 0, 0, 0);
;     p1 = __builtin_amdgcn_mfma_f32_32x32x16_bf16(b1, qr[d0], p1, 0, 0, 0); }
; template <int DQK, bool FIX>
; __device__ __forceinline__ void attn_item(const bf16* Qb, const bf16* __restrict__ Kh, const bf16* __restrict__ Vh,
;                                           u16* Ob, int q0, int L, int NT, char* lds, float mC) {
;     ...
;     __syncthreads(); SWAIT(); SWRITE(0, SE);
;     if (act) { RESC(alB); } __syncthreads();
;     if (act) { SBAR(); qkt<DQK>(pA0, pA1, K_lds, qr, r32, hi, (j + 1) * KVBLK, L);
;       finishSM(pB0, pB1, alB, l_reg, pa0, pa1, pa2, pa3); SBAR(); }
;     if (j + 3 < NT) SLOAD(SE, (j + 3) * KVBLK); SBAR();
.LBB0_895:
	s_or_b64 exec, exec, s[2:3]
	s_waitcnt lgkmcnt(0)
	s_barrier
	s_waitcnt vmcnt(2)
	s_waitcnt vmcnt(3)
	ds_write_b128 v193, v[144:147]
	s_waitcnt vmcnt(2)
	ds_write_b128 v194, v[148:151] offset:49152
	s_and_saveexec_b64 s[2:3], s[8:9]
	ds_write_b128 v195, v[136:139] offset:49152
	s_or_b64 exec, exec, s[2:3]
	s_and_saveexec_b64 s[2:3], s[10:11]
	s_cbranch_execz .LBB0_903
	s_add_i32 s14, s4, 0x80
	s_cmp_le_u32 s14, s5
	s_cbranch_scc0 .Lslow96b
	s_and_b64 vcc, exec, s[12:13]
	s_cbranch_vccz .Lslow96b
	ds_read_b128 v[222:225], v200 offset:32768
	ds_read_b128 v[226:229], v200 offset:40960
	ds_read_b128 v[230:233], v201 offset:32768
	ds_read_b128 v[234:237], v201 offset:40960
	ds_read_b128 v[238:241], v202 offset:32768
	ds_read_b128 v[242:245], v202 offset:40960
	ds_read_b128 v[246:249], v203 offset:32768
	ds_read_b128 v[250:253], v203 offset:40960
	v_cvt_pk_bf16_f32 v10, v80, v81
	v_cvt_pk_bf16_f32 v11, v82, v83
	v_cvt_pk_bf16_f32 v12, v84, v85
	v_cvt_pk_bf16_f32 v13, v86, v87
	v_cvt_pk_bf16_f32 v152, v88, v89
	v_cvt_pk_bf16_f32 v153, v90, v91
	v_cvt_pk_bf16_f32 v154, v92, v93
	v_cvt_pk_bf16_f32 v155, v94, v95
	s_waitcnt lgkmcnt(7)
	v_mfma_f32_32x32x16_bf16 v[64:79], v[222:225], v[112:115], 0
	ds_read_b128 v[222:225], v204 offset:32768
	ds_read_b64_tr_b16 v[206:207], v199 offset:0
	ds_read_b64_tr_b16 v[208:209], v199 offset:2048
	ds_read_b64_tr_b16 v[210:211], v199 offset:4096
	ds_read_b64_tr_b16 v[212:213], v199 offset:6144
	v_exp_f32_e32 v96, v96
	v_exp_f32_e32 v97, v97
	v_add_f32_e32 v0, 0, v80
	s_waitcnt lgkmcnt(11)
	v_mfma_f32_32x32x16_bf16 v[48:63], v[226:229], v[112:115], 0
	ds_read_b128 v[226:229], v204 offset:40960
	ds_read_b64_tr_b16 v[214:215], v199 offset:8192
	ds_read_b64_tr_b16 v[216:217], v199 offset:10240
	ds_read_b64_tr_b16 v[218:219], v199 offset:12288
	s_waitcnt lgkmcnt(14)
	ds_read_b64_tr_b16 v[220:221], v199 offset:14336
	v_exp_f32_e32 v98, v98
	v_exp_f32_e32 v99, v99
	v_add_f32_e32 v0, v81, v0
	v_mfma_f32_32x32x16_bf16 v[64:79], v[230:233], v[116:119], v[64:79]
	s_waitcnt lgkmcnt(14)
	ds_read_b128 v[230:233], v205 offset:32768
	v_exp_f32_e32 v100, v100
	v_exp_f32_e32 v101, v101
	v_add_f32_e32 v0, v82, v0
	v_mfma_f32_32x32x16_bf16 v[48:63], v[234:237], v[116:119], v[48:63]
	s_waitcnt lgkmcnt(14)
	ds_read_b128 v[234:237], v205 offset:40960
	v_exp_f32_e32 v102, v102
	v_exp_f32_e32 v103, v103
	v_add_f32_e32 v0, v83, v0
	v_mfma_f32_32x32x16_bf16 v[64:79], v[238:241], v[120:123], v[64:79]
	v_exp_f32_e32 v104, v104
	v_exp_f32_e32 v105, v105
	v_add_f32_e32 v0, v84, v0
	s_waitcnt lgkmcnt(14)
	v_mfma_f32_32x32x16_bf16 v[48:63], v[242:245], v[120:123], v[48:63]
	v_exp_f32_e32 v106, v106
	v_exp_f32_e32 v107, v107
	v_add_f32_e32 v0, v85, v0
	s_waitcnt lgkmcnt(13)
	v_mfma_f32_32x32x16_bf16 v[64:79], v[246:249], v[124:127], v[64:79]
	v_exp_f32_e32 v108, v108
	v_exp_f32_e32 v109, v109
	v_add_f32_e32 v0, v86, v0
	s_waitcnt lgkmcnt(12)
	v_mfma_f32_32x32x16_bf16 v[48:63], v[250:253], v[124:127], v[48:63]
	v_exp_f32_e32 v110, v110
	v_exp_f32_e32 v111, v111
	v_add_f32_e32 v0, v87, v0
	s_waitcnt lgkmcnt(11)
	v_mfma_f32_32x32x16_bf16 v[64:79], v[222:225], v[128:131], v[64:79]
	ds_read_b64_tr_b16 v[238:239], v199 offset:512
	ds_read_b64_tr_b16 v[240:241], v199 offset:2560
	ds_read_b64_tr_b16 v[242:243], v199 offset:4608
	ds_read_b64_tr_b16 v[244:245], v199 offset:6656
	v_cvt_pk_bf16_f32 v156, v96, v97
	v_cvt_pk_bf16_f32 v157, v98, v99
	v_cvt_pk_bf16_f32 v158, v100, v101
	v_cvt_pk_bf16_f32 v159, v102, v103
	v_add_f32_e32 v0, v88, v0
	v_add_f32_e32 v0, v89, v0
	s_waitcnt lgkmcnt(10)
	v_mfma_f32_32x32x16_bf16 v[48:63], v[226:229], v[128:131], v[48:63]
	v_cvt_pk_bf16_f32 v160, v104, v105
	v_cvt_pk_bf16_f32 v161, v106, v107
	v_cvt_pk_bf16_f32 v162, v108, v109
	v_cvt_pk_bf16_f32 v163, v110, v111
	v_add_f32_e32 v0, v90, v0
	v_add_f32_e32 v0, v91, v0
	s_waitcnt lgkmcnt(5)
	v_mfma_f32_32x32x16_bf16 v[64:79], v[230:233], v[132:135], v[64:79]
	ds_read_b64_tr_b16 v[246:247], v199 offset:8704
	ds_read_b64_tr_b16 v[248:249], v199 offset:10752
	ds_read_b64_tr_b16 v[250:251], v199 offset:12800
	ds_read_b64_tr_b16 v[252:253], v199 offset:14848
	v_add_f32_e32 v0, v92, v0
	v_add_f32_e32 v0, v93, v0
	v_add_f32_e32 v0, v94, v0
	v_add_f32_e32 v0, v95, v0
	v_add_f32_e32 v0, v96, v0
	s_waitcnt lgkmcnt(8)
	v_mfma_f32_32x32x16_bf16 v[48:63], v[234:237], v[132:135], v[48:63]
	v_add_f32_e32 v0, v97, v0
	v_add_f32_e32 v0, v98, v0
	v_add_f32_e32 v0, v99, v0
	v_add_f32_e32 v0, v100, v0
	v_add_f32_e32 v0, v101, v0
	s_or_b64 exec, exec, s[2:3]
	s_cmp_ge_u32 s79, s97
	s_cselect_b64 s[2:3], -1, 0
	s_and_b64 vcc, exec, s[2:3]
	s_cbranch_vccnz .Lfast96b_nl
	global_load_dwordx4 v[144:147], v14, s[84:85]
	global_load_dwordx4 v[148:151], v15, s[76:77]
	s_and_saveexec_b64 s[14:15], s[8:9]
	s_cbranch_execz .Lfast96b_k2
	global_load_dwordx4 v[136:139], v188, s[76:77]

; #define SBAR() __builtin_amdgcn_sched_barrier(0)
; #define SLOAD(i, key0) do { sr_[i].v = *reinterpret_cast<const bf16x8*>(&Vh[(long)((key0) + vr) * ldv + vc]); \
;     sr_[i].k0 = *reinterpret_cast<const bf16x8*>(&Kh[(long)((key0) + kr0) * ldk + kc0]); \
;     if (k2) sr_[i].k1 = *reinterpret_cast<const bf16x8*>(&Kh[(long)((key0) + kr1) * ldk + kc1]); } while (0)
; template <int DQK, bool FIX>
; __device__ __forceinline__ void attn_item(const bf16* Qb, const bf16* __restrict__ Kh, const bf16* __restrict__ Vh,
;                                           u16* Ob, int q0, int L, int NT, char* lds, float mC) {
;     ...
;     if (act) { SBAR(); qkt<DQK>(pA0, pA1, K_lds, qr, r32, hi, (j + 1) * KVBLK, L);
;       finishSM(pB0, pB1, alB, l_reg, pa0, pa1, pa2, pa3); SBAR(); }
;     if (j + 3 < NT) SLOAD(SE, (j + 3) * KVBLK); SBAR();
.LBB0_903:
	s_or_b64 exec, exec, s[2:3]
	s_cmp_ge_u32 s79, s97
	s_cselect_b64 s[2:3], -1, 0
	s_and_b64 vcc, exec, s[2:3]
	s_cbranch_vccnz .LBB0_907
	v_lshl_add_u64 v[14:15], v[168:169], 0, s[6:7]
	v_add_co_u32_e32 v14, vcc, 0xa178000, v14
	global_load_dwordx4 v[144:147], v[170:171], off
	s_nop 0
	v_addc_co_u32_e32 v15, vcc, 0, v15, vcc
	global_load_dwordx4 v[148:151], v[14:15], off
	s_and_saveexec_b64 s[14:15], s[8:9]
	s_cbranch_execz .LBB0_906
	v_lshl_add_u64 v[14:15], v[166:167], 0, s[6:7]
	v_add_co_u32_e32 v14, vcc, 0xa178000, v14
	s_nop 1
	v_addc_co_u32_e32 v15, vcc, 0, v15, vcc
	global_load_dwordx4 v[136:139], v[14:15], off

; __device__ __forceinline__ void finishSM(f32x16& p0, f32x16& p1, float alpha, float& l_reg, bf16x8& pa0, bf16x8& pa1, bf16x8& pa2, bf16x8& pa3) {
; #pragma unroll
;   for (int r = 0; r < 16; ++r) p1[r] = __builtin_amdgcn_exp2f(p1[r]);
;   float ps = 0;
; #pragma unroll
;   for (int r = 0; r < 16; ++r) ps += p0[r];
; #pragma unroll
;   for (int r = 0; r < 16; ++r) ps += p1[r];
;   { auto rr = __builtin_amdgcn_permlane32_swap(__float_as_uint(ps), __float_as_uint(ps), false, false);
;     ps = __uint_as_float(rr[0]) + __uint_as_float(rr[1]); }
;   l_reg = l_reg * alpha + ps;
;     ...
;   PK4(p0, 0, pa0); PK4(p0, 8, pa1); PK4(p1, 0, pa2); PK4(p1, 8, pa3);
;     ...
; }
; template <int DQK>
; __device__ __forceinline__ void qkt(f32x16& p0, f32x16& p1, const bf16* Ks, const bf16x8* qr, int r32, int hi, int k0, int L) {
;   p0 = f32x16{}; p1 = f32x16{};
; #pragma unroll
;   for (int d0 = 0; d0 < DQK / 16; ++d0) { int cb = (d0 * 16 + hi * 8) * 2;
;     bf16x8 b0 = *reinterpret_cast<const bf16x8*>((const char*)Ks + KSWZ(r32, cb));
;     bf16x8 b1 = *reinterpret_cast<const bf16x8*>((const char*)Ks + KSWZ(32 + r32, cb));
;     p0 = __builtin_amdgcn_mfma_f32_32x32x16_bf16(b0, qr[d0], p0, 0, 0, 0);
;     p1 = __builtin_amdgcn_mfma_f32_32x32x16_bf16(b1, qr[d0], p1, 0, 0, 0); }
;   if (k0 + KVBLK > L) {
; #pragma unroll
;     for (int r = 0; r < 16; ++r) { const int key = k0 + crow(r, hi);
;       if (key >= L) p0[r] = -1e30f;
;       if (key + 32 >= L) p1[r] = -1e30f; }
;   }
; }
; __device__ __forceinline__ int v_st(int k, int c) { const int kk = (k & ~0xC) | ((k & 4) << 1) | ((k & 8) >> 1); return ((kk >> 3) * 4 + (c >> 5)) * 512 + ((kk & 7) * 32 + (c & 31)) * 2; }
; __device__ __forceinline__ int v_rd_base(int lane) { return ((lane & 3) << 3) | (((lane >> 2) & 3) << 6) | (((lane >> 4) & 1) << 5) | (((lane >> 5) & 1) << 8); }
; template <int OFF> __device__ __forceinline__ s16x4 tr_read(int vb) {
;   s16x4 r; asm volatile("ds_read_b64_tr_b16 %0, %1 offset:%2" : "=&v"(r) : "v"(vb), "i"(OFF) : "memory"); return r;
; template <int DQK, bool FIX>
; __device__ __forceinline__ void attn_item(const bf16* Qb, const bf16* __restrict__ Kh, const bf16* __restrict__ Vh,
;                                           u16* Ob, int q0, int L, int NT, char* lds, float mC) {
;     ...
;   if (NT & 1) {
;     if (act) { finishSM(pA0, pA1, alA, l_reg, pa0, pa1, pa2, pa3); SBAR(); pv_d0(o, vb0, pa0, pa1, pa2, pa3); }
.LBB0_913:
	s_mov_b64 s[74:75], 0x2149c980
	s_mov_b64 s[76:77], 0x21544900
	s_mov_b64 s[80:81], 0x14200180
	s_mov_b64 s[84:85], 0x14200100
	s_and_saveexec_b64 s[2:3], s[10:11]
	s_cbranch_execz .LBB0_915
	v_mov_b32_e32 v187, v186
	s_nop 1
	v_permlane32_swap_b32_e32 v186, v187
	v_add_f32_e32 v186, v186, v187
	v_add_f32_e32 v198, v198, v186
	v_add_f32_e32 v2, 0, v64
	v_add_f32_e32 v2, v65, v2
	v_add_f32_e32 v2, v66, v2
	v_add_f32_e32 v2, v67, v2
	v_add_f32_e32 v2, v68, v2
	v_add_f32_e32 v2, v69, v2
	v_add_f32_e32 v2, v70, v2
	v_add_f32_e32 v2, v71, v2
	v_add_f32_e32 v2, v72, v2
	v_add_f32_e32 v2, v73, v2
	v_add_f32_e32 v2, v74, v2
	v_add_f32_e32 v2, v75, v2
	v_exp_f32_e32 v0, v48
	v_add_f32_e32 v2, v76, v2
	v_exp_f32_e32 v10, v49
	v_add_f32_e32 v2, v77, v2
	v_exp_f32_e32 v11, v50
	v_add_f32_e32 v2, v78, v2
	v_exp_f32_e32 v12, v51
	v_add_f32_e32 v2, v79, v2
	v_exp_f32_e32 v13, v52
	v_add_f32_e32 v2, v0, v2
	v_exp_f32_e32 v14, v53
	v_add_f32_e32 v2, v10, v2
	v_exp_f32_e32 v15, v54
	v_add_f32_e32 v2, v11, v2
	v_exp_f32_e32 v48, v55
	v_add_f32_e32 v2, v12, v2
	v_exp_f32_e32 v49, v56
	v_add_f32_e32 v2, v13, v2
	v_exp_f32_e32 v50, v57
	v_add_f32_e32 v2, v14, v2
	v_exp_f32_e32 v51, v58
	v_add_f32_e32 v2, v15, v2
	v_exp_f32_e32 v52, v59
	v_add_f32_e32 v2, v48, v2
	v_exp_f32_e32 v53, v60
	v_add_f32_e32 v2, v49, v2
	v_exp_f32_e32 v54, v61
	v_add_f32_e32 v2, v50, v2
	v_exp_f32_e32 v55, v62
	v_add_f32_e32 v2, v51, v2
	v_exp_f32_e32 v56, v63
	v_add_f32_e32 v2, v52, v2
	v_add_f32_e32 v2, v53, v2
	v_add_f32_e32 v2, v54, v2
	v_add_f32_e32 v2, v55, v2
	v_add_f32_e32 v2, v56, v2
	v_mov_b32_e32 v3, v2
	s_nop 1
	v_permlane32_swap_b32_e32 v2, v3
	v_add_f32_e32 v2, v2, v3
	v_add_f32_e32 v198, v198, v2
	v_cvt_pk_bf16_f32 v2, v64, v65
	v_cvt_pk_bf16_f32 v3, v66, v67
	v_cvt_pk_bf16_f32 v4, v68, v69
	v_cvt_pk_bf16_f32 v5, v70, v71
	v_cvt_pk_bf16_f32 v6, v72, v73
	v_cvt_pk_bf16_f32 v7, v74, v75
	v_cvt_pk_bf16_f32 v8, v76, v77
	v_cvt_pk_bf16_f32 v9, v78, v79
	v_cvt_pk_bf16_f32 v10, v0, v10
	v_cvt_pk_bf16_f32 v11, v11, v12
	v_cvt_pk_bf16_f32 v12, v13, v14
	v_cvt_pk_bf16_f32 v13, v15, v48
	v_cvt_pk_bf16_f32 v48, v49, v50
	v_cvt_pk_bf16_f32 v49, v51, v52
	v_cvt_pk_bf16_f32 v50, v53, v54
	v_cvt_pk_bf16_f32 v51, v55, v56
	ds_read_b64_tr_b16 v[52:53], v197 offset:0
	ds_read_b64_tr_b16 v[54:55], v197 offset:0x800
	ds_read_b64_tr_b16 v[56:57], v197 offset:0x1000
	ds_read_b64_tr_b16 v[58:59], v197 offset:0x1800
	ds_read_b64_tr_b16 v[60:61], v197 offset:0x2000
	ds_read_b64_tr_b16 v[62:63], v197 offset:0x2800
	ds_read_b64_tr_b16 v[64:65], v197 offset:0x3000
	ds_read_b64_tr_b16 v[66:67], v197 offset:0x3800
	s_waitcnt lgkmcnt(0)
	s_nop 0
	v_mfma_f32_32x32x16_bf16 v[32:47], v[2:5], v[52:55], v[32:47]
	ds_read_b64_tr_b16 v[52:53], v197 offset:0x200
	ds_read_b64_tr_b16 v[54:55], v197 offset:0xa00
	v_mfma_f32_32x32x16_bf16 v[32:47], v[6:9], v[56:59], v[32:47]
	ds_read_b64_tr_b16 v[56:57], v197 offset:0x1200
	ds_read_b64_tr_b16 v[58:59], v197 offset:0x1a00
	v_mfma_f32_32x32x16_bf16 v[32:47], v[10:13], v[60:63], v[32:47]
	ds_read_b64_tr_b16 v[60:61], v197 offset:0x2200
	ds_read_b64_tr_b16 v[62:63], v197 offset:0x2a00
	v_mfma_f32_32x32x16_bf16 v[32:47], v[48:51], v[64:67], v[32:47]
	ds_read_b64_tr_b16 v[64:65], v197 offset:0x3200
	ds_read_b64_tr_b16 v[66:67], v197 offset:0x3a00
	s_waitcnt lgkmcnt(0)
	v_mfma_f32_32x32x16_bf16 v[16:31], v[2:5], v[52:55], v[16:31]
	v_mfma_f32_32x32x16_bf16 v[16:31], v[6:9], v[56:59], v[16:31]
	v_mfma_f32_32x32x16_bf16 v[16:31], v[10:13], v[60:63], v[16:31]
	v_mfma_f32_32x32x16_bf16 v[16:31], v[48:51], v[64:67], v[16:31]
